# w_glu/w_out_c bf16 conversion deferred out of P0: one 64x32 item per wave 1..7 inside the two grid barriers before pass C, two at the pass C start
# speedup vs baseline: 1.0706x; 1.0071x over previous
.LBB0_6:
	s_or_b64 exec, exec, s[0:1]
	v_readlane_b32 s0, v255, 2
	s_ashr_i32 s5, s0, 6
	v_readlane_b32 s0, v255, 7
	s_lshl_b32 s4, s0, 3
	v_readlane_b32 s0, v255, 3
	v_readlane_b32 s1, v255, 4
	s_load_dwordx4 s[8:11], s[0:1], 0x0
	s_load_dwordx2 s[28:29], s[0:1], 0x98
	s_load_dwordx4 s[24:27], s[0:1], 0x88
	s_load_dwordx8 s[16:23], s[0:1], 0x68
	s_load_dwordx2 s[2:3], s[0:1], 0xd0
	s_add_i32 s92, s4, s5
	s_lshl_b32 s48, s97, 3
	s_mov_b32 s98, 0
	s_mov_b32 s99, 0x47ff
	s_cmp_eq_u32 s97, 0x100
	s_cselect_b32 s99, 0x37ff, s99
	v_writelane_b32 v255, s5, 13
	s_cmpk_gt_i32 s92, 0x47ff
	v_and_b32_e32 v162, 63, v163
	s_cbranch_scc1 .LBB0_45
	v_readlane_b32 s30, v255, 13
	s_lshl_b32 s30, s30, 14
.Lp0w_entry:
	v_lshrrev_b32_e32 v1, 5, v162
	v_lshlrev_b32_e32 v2, 2, v163
	s_add_i32 s30, s30, 0
	v_and_b32_e32 v22, 0x7c, v2
	v_mul_u32_u24_e32 v2, 0x84, v1
	v_add3_u32 v58, s30, v22, v2
	v_lshlrev_b32_e32 v2, 3, v162
	v_and_b32_e32 v2, 56, v2
	v_mul_u32_u24_e32 v6, 0x84, v2
	v_lshlrev_b32_e32 v2, 1, v2
	v_mov_b32_e32 v3, 0
	s_load_dwordx4 s[4:7], s[0:1], 0x38
	s_load_dwordx4 s[12:15], s[0:1], 0x50
	s_load_dwordx2 s[34:35], s[0:1], 0x60
	s_load_dwordx2 s[36:37], s[0:1], 0xb8
	s_nop 0
	s_load_dwordx2 s[0:1], s[0:1], 0xa8
	v_lshrrev_b32_e32 v59, 3, v162
	s_waitcnt lgkmcnt(0)
	v_lshl_add_u64 v[12:13], s[2:3], 0, v[2:3]
	s_mov_b64 s[38:39], 0x4a00000
	v_lshl_add_u64 v[4:5], v[12:13], 0, s[38:39]
	v_lshlrev_b32_e32 v2, 2, v59
	s_mov_b64 s[38:39], 0x4200000
	v_add3_u32 v60, s30, v6, v2
	v_lshl_add_u64 v[6:7], v[12:13], 0, s[38:39]
	s_mov_b64 s[38:39], 0x3200000
	v_lshl_add_u64 v[8:9], v[12:13], 0, s[38:39]
	s_mov_b64 s[38:39], 0x2a00000
	v_mov_b32_e32 v23, v3
	s_cmp_lg_u64 s[14:15], 0
	v_lshl_add_u64 v[10:11], v[12:13], 0, s[38:39]
	s_mov_b64 s[38:39], 0xa00000
	v_lshl_add_u64 v[14:15], s[6:7], 0, v[22:23]
	s_cselect_b64 s[6:7], -1, 0
	s_cmp_lg_u64 s[4:5], 0
	v_lshl_or_b32 v64, s92, 7, v2
	v_lshlrev_b32_e32 v2, 1, v59
	s_mov_b32 s31, 0
	v_or_b32_e32 v61, 8, v59
	v_or_b32_e32 v62, 16, v59
	v_or_b32_e32 v63, 24, v59
	v_lshl_add_u64 v[12:13], v[12:13], 0, s[38:39]
	v_lshl_add_u64 v[16:17], s[36:37], 0, v[22:23]
	v_lshl_add_u64 v[18:19], s[0:1], 0, v[22:23]
	v_lshl_add_u64 v[20:21], s[34:35], 0, v[22:23]
	v_lshl_add_u64 v[22:23], s[12:13], 0, v[22:23]
	s_cselect_b64 s[12:13], -1, 0
	s_lshl_b32 s38, s92, 5
	s_lshl_b32 s39, s48, 5
	s_lshl_b32 s40, s48, 7
	v_lshl_or_b32 v65, s92, 6, v2
	s_lshl_b32 s41, s48, 6
	s_mov_b32 s42, 0xc000
	s_movk_i32 s43, 0x7ff
	v_add_u32_e32 v66, 0x400, v58
	v_add_u32_e32 v67, 0x800, v58
	v_add_u32_e32 v68, 0xc00, v58
	v_add_u32_e32 v69, 0x1000, v58
	v_add_u32_e32 v70, 0x1400, v58
	v_add_u32_e32 v71, 0x1800, v58
	v_add_u32_e32 v72, 0x1c00, v58
	s_mov_b32 s44, s92
	s_branch .LBB0_10

.LBB0_9:
	s_add_i32 s44, s44, s48
	s_add_i32 s38, s38, s39
	v_add_u32_e32 v64, s40, v64
	s_cmp_gt_i32 s44, s99
	v_add_u32_e32 v65, s41, v65
	s_cbranch_scc1 .LBB0_45

.LBB0_45:
	s_cmp_lg_u32 s98, 0
	s_cbranch_scc1 .Ltr_b1
	s_cmpk_gt_i32 s92, 0x203f
	v_mbcnt_lo_u32_b32 v1, -1, 0
	s_cbranch_scc1 .LBB0_52
	v_mbcnt_hi_u32_b32 v2, -1, v1
	v_and_b32_e32 v4, 64, v2
	v_add_u32_e32 v4, 64, v4
	v_xor_b32_e32 v5, 1, v2
	v_cmp_lt_i32_e32 vcc, v5, v4
	s_waitcnt lgkmcnt(0)
	s_add_u32 s33, s2, 0x10000
	s_addc_u32 s36, s3, 0
	v_cndmask_b32_e32 v5, v2, v5, vcc
	v_lshlrev_b32_e32 v6, 2, v5
	v_xor_b32_e32 v5, 2, v2
	v_cmp_lt_i32_e32 vcc, v5, v4
	s_add_u32 s37, s2, 0x20000
	s_addc_u32 s38, s3, 0
	v_cndmask_b32_e32 v5, v2, v5, vcc
	v_lshlrev_b32_e32 v7, 2, v5
	v_xor_b32_e32 v5, 4, v2
	v_cmp_lt_i32_e32 vcc, v5, v4
	s_ashr_i32 s93, s92, 31
	v_mov_b32_e32 v3, 0
	v_cndmask_b32_e32 v5, v2, v5, vcc
	v_lshlrev_b32_e32 v8, 2, v5
	v_xor_b32_e32 v5, 8, v2
	v_cmp_lt_i32_e32 vcc, v5, v4
	s_ashr_i32 s49, s48, 31
	s_lshl_b64 s[6:7], s[92:93], 13
	v_cndmask_b32_e32 v5, v2, v5, vcc
	v_lshlrev_b32_e32 v9, 2, v5
	v_xor_b32_e32 v5, 16, v2
	v_cmp_lt_i32_e32 vcc, v5, v4
	s_mov_b64 s[4:5], 0x5200000
	s_add_u32 s8, s8, s6
	v_cndmask_b32_e32 v5, v2, v5, vcc
	v_lshlrev_b32_e32 v10, 2, v5
	v_xor_b32_e32 v5, 32, v2
	v_cmp_lt_i32_e32 vcc, v5, v4
	s_mov_b32 s1, 0
	s_addc_u32 s9, s9, s7
	v_cndmask_b32_e32 v2, v2, v5, vcc
	v_lshlrev_b32_e32 v11, 2, v2
	v_lshlrev_b32_e32 v2, 3, v162
	v_lshl_add_u64 v[4:5], s[2:3], 0, v[2:3]
	v_lshl_add_u64 v[4:5], v[4:5], 0, s[4:5]
	v_cmp_eq_u32_e64 s[4:5], 0, v162
	s_lshl_b64 s[12:13], s[48:49], 13
	v_lshlrev_b32_e32 v2, 4, v162
	s_movk_i32 s39, 0x1000
	v_mov_b32_e32 v12, 0x358637bd
	s_mov_b32 s40, 0xf800000
	v_mov_b32_e32 v13, 0x260
	s_mov_b64 s[14:15], s[92:93]
	s_branch .LBB0_48

.Ltr_f1:
	s_branch .Lp0w_entry

.Ltr_b3:
	s_cmp_eq_u32 s98, 6
	s_cbranch_scc1 .Lb6_ret
	s_branch .Ltr_b4

.LBB0_1256:
	s_waitcnt vmcnt(0)
	s_barrier
	s_cmp_eq_u32 s97, 0x100
	s_cbranch_scc0 .Lb6_skip
	v_readlane_b32 s7, v255, 2
	v_readlane_b32 s6, v255, 7
	s_nop 0
	s_lshr_b32 s7, s7, 6
	s_cmp_eq_u32 s7, 0
	s_cbranch_scc1 .Lb6_skip
	s_mov_b64 s[46:47], exec
	s_mov_b64 exec, -1
	s_add_i32 s92, s7, -1
	s_lshl_b32 s92, s92, 8
	s_add_i32 s92, s92, s6
	s_add_i32 s92, s92, 0x3800
	s_mov_b64 s[100:101], s[4:5]
	s_mov_b32 s98, 6
	s_mov_b32 s99, 0x47ff
	s_movk_i32 s48, 0x1000
	v_readlane_b32 s0, v255, 3
	v_readlane_b32 s1, v255, 4
	v_readlane_b32 s2, v255, 0
	v_readlane_b32 s3, v255, 1
	v_and_b32_e32 v162, 63, v163
	s_lshl_b32 s30, s7, 14
	s_nop 4
	s_branch .Ltr_f3
.Lb6_ret:
	s_mov_b32 s98, 0
	s_mov_b64 s[4:5], s[100:101]
	v_mbcnt_lo_u32_b32 v1, -1, 0
	s_mov_b64 exec, s[46:47]
.Lb6_skip:
	s_mov_b64 s[2:3], exec
	v_readlane_b32 s0, v255, 11
	v_readlane_b32 s1, v255, 12
	s_and_b64 s[0:1], s[2:3], s[0:1]
	s_mov_b64 exec, s[0:1]
	s_cbranch_execz .LBB0_1308
	s_add_i32 s0, 0, 0x20000
	v_mov_b32_e32 v2, s0
	s_waitcnt vmcnt(0) expcnt(0) lgkmcnt(0)
	ds_read_b32 v4, v2
	s_add_i32 s0, 0, 0x20004
	v_mov_b32_e32 v2, s0
	ds_read_b32 v2, v2
	s_waitcnt lgkmcnt(1)
	v_cmp_ne_u32_e32 vcc, 0, v4
	s_cbranch_vccnz .LBB0_1272
	v_readlane_b32 s0, v255, 5
	v_readlane_b32 s1, v255, 6
	s_load_dwordx2 s[8:9], s[0:1], 0x4
	v_readlane_b32 s38, v255, 0
	v_readlane_b32 s39, v255, 1
	s_add_u32 s0, s38, 0x5e0200
	s_addc_u32 s1, s39, 0
	s_add_u32 s6, s38, 0x5e0400
	s_addc_u32 s7, s39, 0
	s_waitcnt lgkmcnt(0)
	s_mul_i32 s33, s8, s97
	s_add_u32 s8, s38, 0x5e0500
	s_mul_i32 s33, s33, s9
	s_addc_u32 s9, s39, 0
	s_add_u32 s10, s38, 0x5e0600
	s_addc_u32 s11, s39, 0
	s_add_u32 s12, s38, 0x5e0700
	s_addc_u32 s13, s39, 0
	s_add_u32 s14, s38, 0x5e0800
	s_addc_u32 s15, s39, 0
	s_add_u32 s16, s38, 0x5e0900
	s_addc_u32 s17, s39, 0
	s_add_u32 s18, s38, 0x5e0a00
	s_addc_u32 s19, s39, 0
	s_add_u32 s20, s38, 0x5e0b00
	s_addc_u32 s21, s39, 0
	s_add_u32 s22, s38, 0x5e0c00
	s_addc_u32 s23, s39, 0
	s_add_u32 s24, s38, 0x5e0d00
	s_addc_u32 s25, s39, 0
	s_add_u32 s26, s38, 0x5e0e00
	s_addc_u32 s27, s39, 0
	s_add_u32 s28, s38, 0x5e0f00
	s_addc_u32 s29, s39, 0
	s_add_u32 s30, s38, 0x5e1000
	s_addc_u32 s31, s39, 0
	s_add_u32 s34, s38, 0x5e1100
	s_addc_u32 s35, s39, 0
	s_add_u32 s36, s38, 0x5e1200
	s_addc_u32 s37, s39, 0
	s_add_u32 s38, s38, 0x5e1300
	s_addc_u32 s39, s39, 0
	s_mov_b32 s46, 1
	v_mov_b32_e32 v18, 0
	s_branch .LBB0_1260

.Ltr_b4:
	s_cmp_eq_u32 s98, 7
	s_cbranch_scc1 .Lb7_ret
	s_branch .Lpc_back2

.LBB0_1334:
	s_cmp_eq_u32 s98, 4
	s_cbranch_scc1 .Lpc_back
	s_waitcnt vmcnt(0)
	s_barrier
	s_cmp_eq_u32 s97, 0x100
	s_cbranch_scc0 .Lb7_skip
	v_readlane_b32 s7, v255, 2
	v_readlane_b32 s6, v255, 7
	s_nop 0
	s_lshr_b32 s7, s7, 6
	s_cmp_eq_u32 s7, 0
	s_cbranch_scc1 .Lb7_skip
	s_mov_b64 s[46:47], exec
	s_mov_b64 exec, -1
	s_add_i32 s92, s7, 6
	s_lshl_b32 s92, s92, 8
	s_add_i32 s92, s92, s6
	s_add_i32 s92, s92, 0x3800
	s_mov_b64 s[100:101], s[4:5]
	s_mov_b32 s98, 7
	s_mov_b32 s99, 0x47ff
	s_movk_i32 s48, 0x1000
	v_readlane_b32 s0, v255, 3
	v_readlane_b32 s1, v255, 4
	v_readlane_b32 s2, v255, 0
	v_readlane_b32 s3, v255, 1
	v_and_b32_e32 v162, 63, v163
	s_lshl_b32 s30, s7, 14
	s_nop 4
	s_branch .Ltr_f4

.Lb7_skip:
	s_mov_b64 s[0:1], exec
	v_readlane_b32 s2, v255, 11
	v_readlane_b32 s3, v255, 12
	s_and_b64 s[2:3], s[0:1], s[2:3]
	s_mov_b64 exec, s[2:3]
	s_cbranch_execz .LBB0_1386
	s_add_i32 s2, 0, 0x20000
	v_mov_b32_e32 v2, s2
	s_waitcnt vmcnt(0) expcnt(0) lgkmcnt(0)
	ds_read_b32 v4, v2
	s_add_i32 s2, 0, 0x20004
	v_mov_b32_e32 v2, s2
	ds_read_b32 v2, v2
	s_waitcnt lgkmcnt(1)
	v_cmp_ne_u32_e32 vcc, 0, v4
	s_cbranch_vccnz .LBB0_1350
	v_readlane_b32 s2, v255, 5
	v_readlane_b32 s3, v255, 6
	s_load_dwordx2 s[8:9], s[2:3], 0x4
	v_readlane_b32 s38, v255, 0
	v_readlane_b32 s39, v255, 1
	s_add_u32 s2, s38, 0x5e0200
	s_addc_u32 s3, s39, 0
	s_add_u32 s6, s38, 0x5e0400
	s_addc_u32 s7, s39, 0
	s_waitcnt lgkmcnt(0)
	s_mul_i32 s33, s8, s97
	s_add_u32 s8, s38, 0x5e0500
	s_mul_i32 s33, s33, s9
	s_addc_u32 s9, s39, 0
	s_add_u32 s10, s38, 0x5e0600
	s_addc_u32 s11, s39, 0
	s_add_u32 s12, s38, 0x5e0700
	s_addc_u32 s13, s39, 0
	s_add_u32 s14, s38, 0x5e0800
	s_addc_u32 s15, s39, 0
	s_add_u32 s16, s38, 0x5e0900
	s_addc_u32 s17, s39, 0
	s_add_u32 s18, s38, 0x5e0a00
	s_addc_u32 s19, s39, 0
	s_add_u32 s20, s38, 0x5e0b00
	s_addc_u32 s21, s39, 0
	s_add_u32 s22, s38, 0x5e0c00
	s_addc_u32 s23, s39, 0
	s_add_u32 s24, s38, 0x5e0d00
	s_addc_u32 s25, s39, 0
	s_add_u32 s26, s38, 0x5e0e00
	s_addc_u32 s27, s39, 0
	s_add_u32 s28, s38, 0x5e0f00
	s_addc_u32 s29, s39, 0
	s_add_u32 s30, s38, 0x5e1000
	s_addc_u32 s31, s39, 0
	s_add_u32 s34, s38, 0x5e1100
	s_addc_u32 s35, s39, 0
	s_add_u32 s36, s38, 0x5e1200
	s_addc_u32 s37, s39, 0
	s_add_u32 s38, s38, 0x5e1300
	s_addc_u32 s39, s39, 0
	s_mov_b32 s46, 1
	v_mov_b32_e32 v18, 0
	s_branch .LBB0_1338

.LBB0_1386:
	s_or_b64 exec, exec, s[0:1]
	v_readlane_b32 s2, v255, 3
	v_readlane_b32 s3, v255, 4
	s_waitcnt lgkmcnt(0)
	v_mov_b32_e32 v2, v0
	v_readlane_b32 s0, v255, 7
	s_barrier
	s_cmpk_gt_i32 s0, 0x3ff
	v_readfirstlane_b32 s6, v2
	s_cbranch_scc1 .LBB0_1414
	s_cmp_eq_u32 s97, 0x100
	s_cbranch_scc0 .Lpc_compiled
	v_readlane_b32 s6, v255, 7
	v_readlane_b32 s7, v255, 2
	s_nop 0
	s_lshr_b32 s7, s7, 6
	s_cmp_lt_u32 s7, 4
	s_cbranch_scc1 .Lpc_smp
	s_cmp_lt_u32 s7, 6
	s_cbranch_scc1 .Lpc_start
	s_add_i32 s7, s7, -6
	s_mov_b64 s[100:101], s[4:5]
	s_mov_b32 s98, 5
	s_mov_b32 s99, 0x47ff
	s_movk_i32 s48, 0x1000
	s_add_i32 s92, s7, 14
	s_lshl_b32 s92, s92, 8
	s_add_i32 s92, s92, s6
	s_add_i32 s92, s92, 0x3800
	v_readlane_b32 s0, v255, 3
	v_readlane_b32 s1, v255, 4
	v_readlane_b32 s2, v255, 0
	v_readlane_b32 s3, v255, 1
	v_and_b32_e32 v162, 63, v163
	s_lshl_b32 s30, s7, 14
	s_nop 4
	s_branch .Ltr_f4
.Lpc_back2:
	s_mov_b32 s98, 0
	s_mov_b64 s[4:5], s[100:101]
	s_mov_b64 exec, -1
	v_mbcnt_lo_u32_b32 v1, -1, 0
	s_branch .Lpc_start
.Lpc_smp:
	s_lshl_b32 s92, s6, 2
	s_add_i32 s92, s92, s7
	s_mov_b32 s98, 4
	s_mov_b64 exec, -1
	v_readlane_b32 s0, v255, 3
	v_readlane_b32 s1, v255, 4
	s_nop 4
	s_load_dwordx4 s[52:55], s[0:1], 0xc8
	s_load_dwordx2 s[2:3], s[0:1], 0xa0
	s_load_dwordx4 s[56:59], s[0:1], 0x28
	s_load_dwordx4 s[60:63], s[0:1], 0x90
	s_waitcnt lgkmcnt(0)
	s_add_u32 s64, s54, 0x5200000
	s_addc_u32 s65, s55, 0
	s_add_u32 s66, s54, 0x30000
	s_addc_u32 s67, s55, 0
	s_branch .LBB0_1315

.Lpc_start:
	s_mov_b64 exec, -1
	v_readlane_b32 s6, v255, 3
	v_readlane_b32 s7, v255, 4
	v_readlane_b32 s46, v255, 7
	v_readlane_b32 s47, v255, 2
	s_nop 4
	s_load_dwordx4 s[8:11], s[6:7], 0xc8
	s_load_dwordx2 s[12:13], s[6:7], 0xa0
	s_lshr_b32 s47, s47, 6
	s_mul_i32 s48, s47, 0x2400
	s_add_i32 s48, s48, 0x6100
	s_mov_b32 s42, -1
	s_mov_b32 s43, 0
	s_mov_b32 s44, 0xffff
	s_mov_b32 s45, 0xffff
	v_and_b32_e32 v209, 63, v0
	v_and_b32_e32 v210, 31, v209
	v_lshrrev_b32_e32 v211, 5, v209
	v_cmp_lt_u32_e64 s[40:41], 31, v209
	v_xor_b32_e32 v199, 32, v209
	v_lshlrev_b32_e32 v199, 2, v199
	v_mul_u32_u24_e32 v200, 0x48, v210
	v_lshl_add_u32 v200, v211, 3, v200
	v_add_u32_e32 v200, s48, v200
	v_and_b32_e32 v212, 15, v209
	v_lshrrev_b32_e32 v213, 2, v212
	v_and_b32_e32 v212, 3, v212
	v_bfe_u32 v214, v209, 4, 1
	v_lshl_add_u32 v213, v211, 3, v213
	v_mul_u32_u24_e32 v201, 0x48, v213
	v_lshl_add_u32 v212, v214, 2, v212
	v_lshl_add_u32 v201, v212, 3, v201
	v_add_u32_e32 v201, s48, v201
	v_lshlrev_b32_e32 v202, 2, v210
	v_lshl_add_u32 v202, v211, 8, v202
	v_add_u32_e32 v202, s48, v202
	v_lshrrev_b32_e32 v212, 1, v209
	v_and_b32_e32 v213, 1, v209
	v_lshlrev_b32_e32 v203, 6, v212
	v_lshl_add_u32 v203, v213, 5, v203
	v_add_u32_e32 v203, s48, v203
	v_lshlrev_b32_e32 v204, 12, v210
	v_lshl_add_u32 v204, v211, 4, v204
	v_lshlrev_b32_e32 v205, 12, v212
	v_lshl_add_u32 v205, v213, 4, v205
	v_lshlrev_b32_e32 v206, 2, v210
	v_lshlrev_b32_e32 v207, 3, v210
	v_lshlrev_b32_e32 v208, 4, v209
	v_lshlrev_b32_e32 v212, 3, v211
	v_sub_u32_e32 v212, v210, v212
	s_waitcnt lgkmcnt(0)
	v_mov_b32_e32 v254, v212
	v_cmp_gt_u32_e64 s[38:39], 16, v210
